# plus: 3.5us stagger of half the workgroups at the gates phase entry
# baseline (speedup 1.0000x reference)
;   DI bf16_t* wt_g() const { return (bf16_t*)(ws + OFF_WT_G); }
;   DI bf16_t* xc() const { return (bf16_t*)(ws + OFF_Q1); }
; DI void phase_gates(const Params& p, char* smem) {
;   u32x4 ra[4], rb[4]; bool pre = false;
;   for (int t = blockIdx.x; t < 64 * 8; t += gridDim.x) {
;     const int mt = t & 63, gi = t >> 6, tn = t + gridDim.x;
;     const bool has_next = tn < 64 * 8;
;     const GTile tl{p.xc() + gi * 128, 1024, p.wt_g(), 128, 128, mt * 256, gi * 256}, nx{p.xc() + (tn >> 6) * 128, 1024, p.wt_g(), 128, 128, (tn & 63) * 256, (tn >> 6) * 256};
;     WAVE_GEOM;
.LBB0_284:
	s_or_b64 exec, exec, s[0:1]
	s_cmpk_lt_i32 s84, 0x200
	s_cselect_b64 s[6:7], -1, 0
	s_bitcmp1_b32 s84, 3
	s_cbranch_scc0 .Lstag_3_0
	s_sleep 127
.Lstag_3_0:
	s_cmpk_gt_i32 s84, 0x1ff
	s_waitcnt lgkmcnt(0)
	s_barrier
	s_cbranch_scc1 .LBB0_568
	s_add_u32 s8, s22, 0x154c0000
	s_addc_u32 s9, s23, 0
	s_add_u32 s18, s22, 0x1900000
	s_addc_u32 s19, s23, 0
	s_add_u32 s10, s22, 0x1e6c0000
	s_addc_u32 s11, s23, 0
	s_add_u32 s12, s20, 0x4000000
	s_addc_u32 s13, s21, 0
	s_add_i32 s0, s84, s96
	s_lshl_b32 s24, s84, 8
	s_lshl_b32 s25, s96, 8
	s_lshl_b32 s34, s0, 18
	s_lshl_b32 s35, s96, 18
	s_mov_b64 s[2:3], 0
	v_mov_b32_e32 v185, 0
	s_mov_b32 s36, 0x20000
	s_mov_b32 s37, 0x40000
	s_mov_b32 s38, 0x60000
	s_movk_i32 s39, 0x4000
	s_mov_b32 s40, 0x8000
	s_mov_b32 s41, 0xc000
	s_movk_i32 s42, 0x90
	s_mov_b64 s[14:15], 0x20000
	s_mov_b64 s[26:27], 0x4000
	s_mov_b64 s[28:29], 0x40000
	s_mov_b64 s[30:31], 0x8000
	s_mov_b32 s43, 0xbe99999a
	v_mov_b32_e32 v188, 0x3d2aaaab
	s_mov_b32 s44, 0xf800000
	v_mov_b32_e32 v189, 0x260
	s_mov_b32 s45, s84
	s_branch .LBB0_287
